# P3 queue order LPT-style: heavy attention, conv, mid attention, weight copies, lightest attention, on p3d
# baseline (speedup 1.0000x reference)
; template<int THRL,class Extra> __device__ __forceinline__ void attn_phase_dyn(char*lds,const AttnTensors&T,unsigned*ctr,const Extra&X,int nextra){
;     ...
;   for(;;){
;     if(tid==0){uw[0]=nxt;}
;     asm volatile("s_waitcnt lgkmcnt(0)\n\ts_barrier":::"memory");
;     const unsigned u=(unsigned)__builtin_amdgcn_readfirstlane((int)uw[0]);
;     if(u>=(unsigned)(BATCH*NHEAD*NQB+nextra))break;
;     if(u>=(unsigned)(BATCH*NHEAD*NQB)){ if(tid==0)nxt=G_+__hip_atomic_fetch_add(ctr,1u,__ATOMIC_RELAXED,__HIP_MEMORY_SCOPE_AGENT);
;       X((int)u-BATCH*NHEAD*NQB); asm volatile("s_waitcnt lgkmcnt(0)\n\ts_barrier":::"memory"); continue; }
;     const int qb=NQB-1-(int)(u/(BATCH*NHEAD)), bh=(int)(u%(BATCH*NHEAD));
.LBB0_343:
	s_and_saveexec_b64 s[6:7], s[18:19]
	ds_write_b32 v201, v213 offset:49152
	s_or_b64 exec, exec, s[6:7]
	s_waitcnt lgkmcnt(0)
	s_barrier
	ds_read_b32 v1, v201 offset:49152
	s_mov_b64 s[6:7], -1
	s_waitcnt lgkmcnt(0)
	v_readfirstlane_b32 s63, v1
	s_cmpk_lt_u32 s63, 0x300
	s_cbranch_scc1 .Lqmap_done
	s_cmpk_gt_u32 s63, 0x57f
	s_cbranch_scc1 .Lqmap_done
	s_add_i32 s80, s63, 0x100
	s_cmpk_lt_u32 s63, 0x400
	s_cbranch_scc1 .Lqmap_set
	s_add_i32 s80, s63, 0xffffff00
	s_cmpk_lt_u32 s63, 0x480
	s_cbranch_scc1 .Lqmap_set
	s_add_i32 s80, s63, 0x80
	s_cmpk_lt_u32 s63, 0x500
	s_cbranch_scc1 .Lqmap_set
	s_add_i32 s80, s63, 0xfffffe80
